# MLA attention loop: rescale decision branches on the wave-uniform ballot first (alpha=1 fast path, new-max/exp/select out of line, asm guide 7.12) and the first four K fragment reads are issued ahead
# speedup vs baseline: 1.0425x; 1.0014x over previous
.LBB0_514:
	s_lshl_b32 s33, s18, 14
	v_add3_u32 v224, s33, v156, v155
	v_add3_u32 v225, s33, v157, v155
	ds_read_b128 v[170:173], v224 offset:40960
	ds_read_b128 v[174:177], v225 offset:40960
	ds_read_b128 v[178:181], v225 offset:32768
	ds_read_b128 v[182:185], v224 offset:32768
	s_andn2_b64 vcc, exec, s[4:5]
	s_add_i32 s31, s19, 1
	s_cbranch_vccnz .LBB0_516
	v_mov_b32_e32 v2, s31
	v_sub_co_u32_e64 v68, vcc, s19, 63
	s_and_b64 s[4:5], vcc, exec
	s_nop 0
	v_cndmask_b32_e32 v2, v68, v2, vcc
	s_mov_b32 s19, 0x30000
	s_cselect_b32 s5, s17, s26
	s_cselect_b32 s4, s16, s25
	s_cselect_b32 s35, s24, s28
	s_cselect_b32 s34, s23, s27
	v_mul_hi_u32 v69, v2, s19
	v_mul_lo_u32 v68, v2, s19
	s_lshl_b32 s33, s18, 14
	v_lshl_add_u64 v[68:69], s[4:5], 0, v[68:69]
	s_xor_b32 s4, s33, 0x4000
	v_lshlrev_b64 v[70:71], 18, v[2:3]
	s_add_i32 s4, s29, s4
	v_lshl_add_u64 v[72:73], v[134:135], 1, v[68:69]
	v_mov_b32_e32 v145, v3
	v_lshl_add_u64 v[70:71], s[34:35], 0, v[70:71]
	s_add_i32 m0, s4, 0x8000
	v_lshl_add_u64 v[72:73], v[72:73], 0, v[144:145]
	global_load_lds_dwordx4 v[72:73], off
	v_lshl_add_u64 v[72:73], v[140:141], 1, v[70:71]
	v_mov_b32_e32 v147, v3
	v_lshl_add_u64 v[72:73], v[72:73], 0, v[146:147]
	s_mov_b32 m0, s4
	v_mov_b32_e32 v151, v3
	global_load_lds_dwordx4 v[72:73], off
	v_lshl_add_u64 v[72:73], v[136:137], 1, v[68:69]
	v_lshl_add_u64 v[72:73], v[72:73], 0, v[150:151]
	s_add_i32 m0, s4, 0xa000
	v_lshl_add_u64 v[68:69], v[138:139], 1, v[68:69]
	v_mov_b32_e32 v153, v3
	global_load_lds_dwordx4 v[72:73], off
	v_lshl_add_u64 v[70:71], v[142:143], 1, v[70:71]
	s_add_i32 m0, s4, 0x2000
	v_lshl_add_u64 v[68:69], v[68:69], 0, v[152:153]
	s_mov_b64 s[4:5], 0x100
	s_lshl_b32 s34, s18, 13
	v_lshl_add_u64 v[70:71], v[70:71], 0, v[146:147]
	v_lshl_add_u64 v[68:69], v[68:69], 0, s[4:5]
	s_xor_b32 s4, s34, 0x2000
	global_load_lds_dwordx4 v[70:71], off
	s_add_i32 m0, s30, s4
	s_nop 0
	global_load_lds_dwordx4 v[68:69], off
.LBB0_516:
	s_add_i32 s4, s33, 0
	s_add_i32 s5, s34, 0
	s_add_i32 s5, s5, 0x10000
	s_waitcnt lgkmcnt(2)
	v_mfma_f32_32x32x16_bf16 v[68:83], v[170:173], v[100:103], 0
	v_mfma_f32_32x32x16_bf16 v[68:83], v[174:177], v[104:107], v[68:83]
	v_add3_u32 v2, s4, v158, v155
	v_add3_u32 v145, s4, v160, v155
	ds_read_b128 v[170:173], v2 offset:32768
	ds_read_b128 v[174:177], v145 offset:32768
	s_waitcnt lgkmcnt(2)
	v_mfma_f32_32x32x16_bf16 v[84:99], v[178:181], v[104:107], 0
	v_mfma_f32_32x32x16_bf16 v[84:99], v[182:185], v[100:103], v[84:99]
	ds_read_b128 v[178:181], v145 offset:40960
	ds_read_b128 v[182:185], v2 offset:40960
	s_waitcnt lgkmcnt(2)
	v_mfma_f32_32x32x16_bf16 v[84:99], v[170:173], v[108:111], v[84:99]
	v_mfma_f32_32x32x16_bf16 v[84:99], v[174:177], v[112:115], v[84:99]
	v_add3_u32 v2, s4, v161, v155
	v_add3_u32 v145, s4, v162, v155
	ds_read_b128 v[170:173], v2 offset:40960
	ds_read_b128 v[174:177], v145 offset:40960
	s_waitcnt lgkmcnt(2)
	v_mfma_f32_32x32x16_bf16 v[68:83], v[178:181], v[112:115], v[68:83]
	v_mfma_f32_32x32x16_bf16 v[68:83], v[182:185], v[108:111], v[68:83]
	ds_read_b128 v[178:181], v145 offset:32768
	ds_read_b128 v[182:185], v2 offset:32768
	s_waitcnt lgkmcnt(2)
	v_mfma_f32_32x32x16_bf16 v[68:83], v[170:173], v[116:119], v[68:83]
	v_mfma_f32_32x32x16_bf16 v[68:83], v[174:177], v[120:123], v[68:83]
	v_add3_u32 v2, s4, v163, v155
	v_add3_u32 v145, s4, v164, v155
	ds_read_b128 v[170:173], v2 offset:32768
	ds_read_b128 v[174:177], v145 offset:32768
	s_waitcnt lgkmcnt(2)
	v_mfma_f32_32x32x16_bf16 v[84:99], v[178:181], v[120:123], v[84:99]
	v_mfma_f32_32x32x16_bf16 v[84:99], v[182:185], v[116:119], v[84:99]
	ds_read_b128 v[178:181], v145 offset:40960
	ds_read_b128 v[182:185], v2 offset:40960
	s_waitcnt lgkmcnt(2)
	v_mfma_f32_32x32x16_bf16 v[84:99], v[170:173], v[124:127], v[84:99]
	v_mfma_f32_32x32x16_bf16 v[84:99], v[174:177], v[128:131], v[84:99]
	v_add3_u32 v2, s5, v156, v165
	v_add3_u32 v145, s5, v157, v165
	ds_read_b128 v[170:173], v2 offset:4096
	ds_read_b128 v[174:177], v145 offset:4096
	s_waitcnt lgkmcnt(2)
	v_mfma_f32_32x32x16_bf16 v[68:83], v[178:181], v[128:131], v[68:83]
	v_mfma_f32_32x32x16_bf16 v[68:83], v[182:185], v[124:127], v[68:83]
	ds_read_b128 v[178:181], v145
	ds_read_b128 v[182:185], v2
	s_waitcnt lgkmcnt(2)
	v_mfma_f32_32x32x16_bf16 v[68:83], v[170:173], v[186:189], v[68:83]
	v_mfma_f32_32x32x16_bf16 v[68:83], v[174:177], v[190:193], v[68:83]
	v_add3_u32 v2, s5, v158, v165
	v_add3_u32 v145, s5, v160, v165
	ds_read_b128 v[170:173], v2
	ds_read_b128 v[174:177], v145
	s_waitcnt lgkmcnt(2)
	v_mfma_f32_32x32x16_bf16 v[84:99], v[178:181], v[190:193], v[84:99]
	v_mfma_f32_32x32x16_bf16 v[84:99], v[182:185], v[186:189], v[84:99]
	ds_read_b128 v[178:181], v145 offset:4096
	ds_read_b128 v[182:185], v2 offset:4096
	s_waitcnt lgkmcnt(2)
	v_mfma_f32_32x32x16_bf16 v[84:99], v[170:173], v[194:197], v[84:99]
	v_mfma_f32_32x32x16_bf16 v[84:99], v[174:177], v[204:207], v[84:99]
	s_mov_b32 s4, 0x42ddb3d8
	s_waitcnt lgkmcnt(0)
	v_mfma_f32_32x32x16_bf16 v[68:83], v[178:181], v[204:207], v[68:83]
	v_mfma_f32_32x32x16_bf16 v[68:83], v[182:185], v[194:197], v[68:83]
	s_nop 10
	v_max_f32_e32 v2, v84, v85
	v_max3_f32 v2, v2, v86, v87
	v_max3_f32 v2, v2, v88, v89
	v_max3_f32 v2, v2, v90, v91
	v_max3_f32 v2, v2, v92, v93
	v_max3_f32 v2, v2, v94, v95
	v_max3_f32 v2, v2, v96, v97
	v_max3_f32 v2, v2, v98, v99
	v_max3_f32 v2, v2, v68, v69
	v_max3_f32 v2, v2, v70, v71
	v_max3_f32 v2, v2, v72, v73
	v_max3_f32 v2, v2, v74, v75
	v_max3_f32 v2, v2, v76, v77
	v_max3_f32 v2, v2, v78, v79
	v_max3_f32 v2, v2, v80, v81
	v_max3_f32 v2, v2, v82, v83
	v_mov_b32_e32 v145, v2
	s_nop 1
	v_permlane32_swap_b32_e32 v2, v145
	v_max_f32_e32 v2, v2, v145
	v_sub_f32_e32 v145, v2, v167
	v_cmp_ge_f32_e32 vcc, s4, v145
	s_cmp_eq_u64 vcc, exec
	s_cbranch_scc0 .Lmla_resc_slow
	v_mov_b32_e32 v2, 1.0
	s_mov_b64 s[4:5], -1

.Lmla_resc_slow:
	v_max_f32_e32 v145, v167, v2
	v_sub_f32_e32 v2, v167, v145
	v_mul_f32_e32 v2, 0x3dd53b94, v2
	v_exp_f32_e32 v2, v2
	s_mov_b64 s[4:5], 0
	s_nop 0
	v_cmp_gt_f32_e32 vcc, 1.0, v2
	s_cbranch_vccz .LBB0_520
	s_and_saveexec_b64 s[18:19], s[0:1]
	ds_write_b32 v159, v2 offset:128
	s_or_b64 exec, exec, s[18:19]
	s_waitcnt lgkmcnt(0)
	ds_read_b128 v[170:173], v154 offset:224
	ds_read_b128 v[174:177], v154 offset:192
	ds_read_b128 v[178:181], v154 offset:160
	ds_read_b128 v[182:185], v154 offset:128
	s_waitcnt lgkmcnt(0)
	v_pk_mul_f32 v[66:67], v[66:67], v[172:173]
	v_pk_mul_f32 v[62:63], v[62:63], v[176:177]
	v_pk_mul_f32 v[58:59], v[58:59], v[180:181]
	v_pk_mul_f32 v[54:55], v[54:55], v[184:185]
	v_pk_mul_f32 v[64:65], v[64:65], v[170:171]
	v_pk_mul_f32 v[60:61], v[60:61], v[174:175]
	v_pk_mul_f32 v[56:57], v[56:57], v[178:179]
	v_pk_mul_f32 v[52:53], v[52:53], v[182:183]
	v_pk_mul_f32 v[50:51], v[50:51], v[172:173]
	v_pk_mul_f32 v[46:47], v[46:47], v[176:177]
	v_pk_mul_f32 v[42:43], v[42:43], v[180:181]
	v_pk_mul_f32 v[38:39], v[38:39], v[184:185]
	v_pk_mul_f32 v[48:49], v[48:49], v[170:171]
	v_pk_mul_f32 v[44:45], v[44:45], v[174:175]
	v_pk_mul_f32 v[40:41], v[40:41], v[178:179]
	v_pk_mul_f32 v[36:37], v[36:37], v[182:183]
	v_pk_mul_f32 v[34:35], v[34:35], v[172:173]
	v_pk_mul_f32 v[30:31], v[30:31], v[176:177]
	v_pk_mul_f32 v[26:27], v[26:27], v[180:181]
	v_pk_mul_f32 v[22:23], v[22:23], v[184:185]
	v_pk_mul_f32 v[32:33], v[32:33], v[170:171]
	v_pk_mul_f32 v[28:29], v[28:29], v[174:175]
	v_pk_mul_f32 v[24:25], v[24:25], v[178:179]
	v_pk_mul_f32 v[20:21], v[20:21], v[182:183]
	v_pk_mul_f32 v[18:19], v[18:19], v[172:173]
	v_pk_mul_f32 v[14:15], v[14:15], v[176:177]
	v_pk_mul_f32 v[10:11], v[10:11], v[180:181]
	v_pk_mul_f32 v[6:7], v[6:7], v[184:185]
	v_pk_mul_f32 v[16:17], v[16:17], v[170:171]
	v_pk_mul_f32 v[12:13], v[12:13], v[174:175]
	v_pk_mul_f32 v[8:9], v[8:9], v[178:179]
	v_pk_mul_f32 v[4:5], v[4:5], v[182:183]
	s_branch .LBB0_520
